# final_k plus first output-reduction level written straight into the kept registers (no aligning moves)
# baseline (speedup 1.0000x reference)
; #define LDS_WAIT() asm volatile("s_waitcnt lgkmcnt(0)" ::: "memory")
; __device__ __forceinline__ void attn_query8(const unsigned char* __restrict__ KV8, const bf16_t* __restrict__ Z, const int* __restrict__ SEL, bf16_t* __restrict__ YMIX, int t, LAS float* sbuf  ) {
;     ...
;     for (int h = 0; h < 8; ++h) {
;         float sv[4]; float mx = -__builtin_inff();
; #pragma unroll
;         for (int jj = 0; jj < 4; ++jj) { const int j = lane + 64 * jj; const float s = sbuf[h * 256 + j]; sv[jj] = (j < nsel) ? s : -__builtin_inff(); mx = fmaxf(mx, sv[jj]); }
;         mx = wave_max(mx); float sm = 0.f;
; #pragma unroll
;         for (int jj = 0; jj < 4; ++jj) { const int j = lane + 64 * jj; sv[jj] = (j < nsel) ? __expf(sv[jj] - mx) : 0.f; sm += sv[jj]; }
;         sm = wave_sum(sm); const float inv = 1.f / sm;
; #pragma unroll
;         for (int jj = 0; jj < 4; ++jj) sbuf[h * 256 + lane + 64 * jj] = sv[jj] * inv;
;     }
;     LDS_WAIT();
;     f32x2v o[8];
; #pragma unroll
;     for (int i = 0; i < 8; ++i) o[i] = (f32x2v){0.f, 0.f};
; #pragma unroll 1
;     for (int b = 0; b < nb; b += 3) {
;         kv8_issue(C, rs, lvo, 1024, iv, CLAMPB(b + 2));
;         kv8_pv(A, o, srow, b);
.Latt_nomask:
	v_max3_f32 v134, v150, v151, v152
	v_max3_f32 v134, v134, v153, v154
	v_max3_f32 v134, v134, v155, v156
	v_max3_f32 v134, v134, v157, v158
	v_max3_f32 v134, v134, v159, v160
	v_max3_f32 v134, v134, v161, v162
	v_max3_f32 v134, v134, v163, v164
	v_max3_f32 v134, v134, v165, v166
	v_max3_f32 v134, v134, v167, v168
	v_max3_f32 v134, v134, v169, v170
	v_max3_f32 v134, v134, v171, v172
	v_max3_f32 v134, v134, v173, v174
	v_max3_f32 v134, v134, v175, v176
	v_max3_f32 v134, v134, v177, v178
	v_max3_f32 v134, v134, v179, v180
	v_max_f32_e32 v134, v134, v181
	s_nop 1
	v_max_f32_dpp v135, v134, v134 row_ror:8 row_mask:0xf bank_mask:0xf
	v_max_f32_dpp v134, v134, v134 row_ror:8 row_mask:0xf bank_mask:0xf
	s_nop 1
	v_permlane16_swap_b32_e32 v134, v135
	v_max_f32_e32 v136, v134, v135
	v_max_f32_e32 v134, v134, v135
	s_nop 1
	v_permlane32_swap_b32_e32 v134, v136
	v_max_f32_e32 v134, v134, v136
	v_mul_f32_e32 v134, 0xbfb8aa3b, v134
	v_fma_f32 v150, v150, s28, v134
	v_fma_f32 v151, v151, s28, v134
	v_fma_f32 v152, v152, s28, v134
	v_fma_f32 v153, v153, s28, v134
	v_fma_f32 v154, v154, s28, v134
	v_fma_f32 v155, v155, s28, v134
	v_fma_f32 v156, v156, s28, v134
	v_fma_f32 v157, v157, s28, v134
	v_fma_f32 v158, v158, s28, v134
	v_fma_f32 v159, v159, s28, v134
	v_fma_f32 v160, v160, s28, v134
	v_fma_f32 v161, v161, s28, v134
	v_fma_f32 v162, v162, s28, v134
	v_fma_f32 v163, v163, s28, v134
	v_fma_f32 v164, v164, s28, v134
	v_fma_f32 v165, v165, s28, v134
	v_fma_f32 v166, v166, s28, v134
	v_fma_f32 v167, v167, s28, v134
	v_fma_f32 v168, v168, s28, v134
	v_fma_f32 v169, v169, s28, v134
	v_fma_f32 v170, v170, s28, v134
	v_fma_f32 v171, v171, s28, v134
	v_fma_f32 v172, v172, s28, v134
	v_fma_f32 v173, v173, s28, v134
	v_fma_f32 v174, v174, s28, v134
	v_fma_f32 v175, v175, s28, v134
	v_fma_f32 v176, v176, s28, v134
	v_fma_f32 v177, v177, s28, v134
	v_fma_f32 v178, v178, s28, v134
	v_fma_f32 v179, v179, s28, v134
	v_fma_f32 v180, v180, s28, v134
	v_fma_f32 v181, v181, s28, v134
	v_exp_f32_e32 v150, v150
	v_exp_f32_e32 v151, v151
	v_exp_f32_e32 v152, v152
	v_exp_f32_e32 v153, v153
	v_exp_f32_e32 v154, v154
	v_exp_f32_e32 v155, v155
	v_exp_f32_e32 v156, v156
	v_exp_f32_e32 v157, v157
	v_exp_f32_e32 v158, v158
	v_exp_f32_e32 v159, v159
	v_exp_f32_e32 v160, v160
	v_exp_f32_e32 v161, v161
	v_exp_f32_e32 v162, v162
	v_exp_f32_e32 v163, v163
	v_exp_f32_e32 v164, v164
	v_exp_f32_e32 v165, v165
	v_exp_f32_e32 v166, v166
	v_exp_f32_e32 v167, v167
	v_exp_f32_e32 v168, v168
	v_exp_f32_e32 v169, v169
	v_exp_f32_e32 v170, v170
	v_exp_f32_e32 v171, v171
	v_exp_f32_e32 v172, v172
	v_exp_f32_e32 v173, v173
	v_exp_f32_e32 v174, v174
	v_exp_f32_e32 v175, v175
	v_exp_f32_e32 v176, v176
	v_exp_f32_e32 v177, v177
	v_exp_f32_e32 v178, v178
	v_exp_f32_e32 v179, v179
	v_exp_f32_e32 v180, v180
	v_exp_f32_e32 v181, v181
	s_nop 0
	v_add_f32_e32 v134, v150, v151
	v_add_f32_e32 v134, v134, v152
	v_add_f32_e32 v134, v134, v153
	v_add_f32_e32 v134, v134, v154
	v_add_f32_e32 v134, v134, v155
	v_add_f32_e32 v134, v134, v156
	v_add_f32_e32 v134, v134, v157
	v_add_f32_e32 v134, v134, v158
	v_add_f32_e32 v134, v134, v159
	v_add_f32_e32 v134, v134, v160
	v_add_f32_e32 v134, v134, v161
	v_add_f32_e32 v134, v134, v162
	v_add_f32_e32 v134, v134, v163
	v_add_f32_e32 v134, v134, v164
	v_add_f32_e32 v134, v134, v165
	v_add_f32_e32 v134, v134, v166
	v_add_f32_e32 v134, v134, v167
	v_add_f32_e32 v134, v134, v168
	v_add_f32_e32 v134, v134, v169
	v_add_f32_e32 v134, v134, v170
	v_add_f32_e32 v134, v134, v171
	v_add_f32_e32 v134, v134, v172
	v_add_f32_e32 v134, v134, v173
	v_add_f32_e32 v134, v134, v174
	v_add_f32_e32 v134, v134, v175
	v_add_f32_e32 v134, v134, v176
	v_add_f32_e32 v134, v134, v177
	v_add_f32_e32 v134, v134, v178
	v_add_f32_e32 v134, v134, v179
	v_add_f32_e32 v134, v134, v180
	v_add_f32_e32 v134, v134, v181
	s_nop 1
	v_add_f32_dpp v135, v134, v134 row_ror:8 row_mask:0xf bank_mask:0xf
	v_add_f32_dpp v134, v134, v134 row_ror:8 row_mask:0xf bank_mask:0xf
	s_nop 1
	v_permlane16_swap_b32_e32 v134, v135
	v_add_f32_e32 v136, v134, v135
	v_add_f32_e32 v134, v134, v135
	s_nop 1
	v_permlane32_swap_b32_e32 v134, v136
	v_add_f32_e32 v134, v134, v136
	v_div_scale_f32 v132, s[8:9], v134, v134, 1.0
	v_rcp_f32_e32 v135, v132
	v_div_scale_f32 v133, vcc, 1.0, v134, 1.0
	v_fma_f32 v136, -v132, v135, 1.0
	v_fmac_f32_e32 v135, v136, v135
	v_mul_f32_e32 v136, v133, v135
	v_fma_f32 v137, -v132, v136, v133
	v_fmac_f32_e32 v136, v137, v135
	v_fma_f32 v132, -v132, v136, v133
	s_nop 1
	v_div_fmas_f32 v132, v132, v135, v136
	v_div_fixup_f32 v134, v132, v134, 1.0
	v_mov_b32_e32 v149, v134
	s_waitcnt vmcnt(31)
	ds_write_b32 v148, v240 offset:0
	ds_write_b32 v148, v241 offset:32
	ds_write_b32 v148, v242 offset:64
	ds_write_b32 v148, v243 offset:96
	v_cvt_pk_f32_fp8_e32 v[214:215], v0
	v_cvt_pk_f32_fp8_sdwa v[216:217], v0 src0_sel:WORD_1
	v_pk_mul_f32 v[198:199], v[150:151], v[214:215] op_sel_hi:[0,1]
	v_pk_mul_f32 v[200:201], v[150:151], v[216:217] op_sel_hi:[0,1]
	v_cvt_pk_f32_fp8_e32 v[218:219], v1
	v_cvt_pk_f32_fp8_sdwa v[220:221], v1 src0_sel:WORD_1
	v_pk_mul_f32 v[202:203], v[150:151], v[218:219] op_sel_hi:[0,1]
	v_pk_mul_f32 v[204:205], v[150:151], v[220:221] op_sel_hi:[0,1]
	v_cvt_pk_f32_fp8_e32 v[214:215], v2
	v_cvt_pk_f32_fp8_sdwa v[216:217], v2 src0_sel:WORD_1
	v_pk_mul_f32 v[206:207], v[150:151], v[214:215] op_sel_hi:[0,1]
	v_pk_mul_f32 v[208:209], v[150:151], v[216:217] op_sel_hi:[0,1]
	v_cvt_pk_f32_fp8_e32 v[218:219], v3
	v_cvt_pk_f32_fp8_sdwa v[220:221], v3 src0_sel:WORD_1
	v_pk_mul_f32 v[210:211], v[150:151], v[218:219] op_sel_hi:[0,1]
	v_pk_mul_f32 v[212:213], v[150:151], v[220:221] op_sel_hi:[0,1]
	s_waitcnt vmcnt(30)
; #define LAS __attribute__((address_space(3)))
; __device__ __forceinline__ void kv8_issue(u32x4 (&buf)[8], __amdgpu_buffer_rsrc_t rs, int voff  , int sbase  , const int (&iv)[4], int b) {
;     const int jj = b >> 3, l0 = (b & 7) * 8;
;     const int ivb = (jj == 0) ? iv[0] : (jj == 1) ? iv[1] : (jj == 2) ? iv[2] : iv[3];
; #pragma unroll
;     for (int u = 0; u < 8; ++u) { const int si = __builtin_amdgcn_readlane(ivb, l0 + u); buf[u] = __builtin_amdgcn_raw_buffer_load_b128(rs, voff, si * 2048 + sbase, KV8_AUX); }
; }
; __device__ __forceinline__ void kv8_pv(const u32x4 (&buf)[8], f32x2v (&o2)[8], const LAS float* srow, int b) {
;     const LAS f32x4* p4 = (const LAS f32x4*)(srow + b * 8);
;     const f32x4 p0 = p4[0], p1 = p4[1];
;     const float p[8] = {p0.x, p0.y, p0.z, p0.w, p1.x, p1.y, p1.z, p1.w};
; #pragma unroll
;     for (int u = 0; u < 8; ++u) {
;         const u32x4 v = buf[u]; const f32x2v pp = {p[u], p[u]};
;         o2[0] = __builtin_elementwise_fma(pp, __builtin_amdgcn_cvt_pk_f32_fp8(v.x, false), o2[0]); o2[1] = __builtin_elementwise_fma(pp, __builtin_amdgcn_cvt_pk_f32_fp8(v.x, true), o2[1]);
;         o2[2] = __builtin_elementwise_fma(pp, __builtin_amdgcn_cvt_pk_f32_fp8(v.y, false), o2[2]); o2[3] = __builtin_elementwise_fma(pp, __builtin_amdgcn_cvt_pk_f32_fp8(v.y, true), o2[3]);
;         o2[4] = __builtin_elementwise_fma(pp, __builtin_amdgcn_cvt_pk_f32_fp8(v.z, false), o2[4]); o2[5] = __builtin_elementwise_fma(pp, __builtin_amdgcn_cvt_pk_f32_fp8(v.z, true), o2[5]);
;         o2[6] = __builtin_elementwise_fma(pp, __builtin_amdgcn_cvt_pk_f32_fp8(v.w, false), o2[6]); o2[7] = __builtin_elementwise_fma(pp, __builtin_amdgcn_cvt_pk_f32_fp8(v.w, true), o2[7]);
;     }
	v_cvt_pk_f32_fp8_e32 v[214:215], v4
	v_cvt_pk_f32_fp8_sdwa v[216:217], v4 src0_sel:WORD_1
	v_pk_fma_f32 v[198:199], v[150:151], v[214:215], v[198:199] op_sel:[1,0,0]
	v_pk_fma_f32 v[200:201], v[150:151], v[216:217], v[200:201] op_sel:[1,0,0]
	v_cvt_pk_f32_fp8_e32 v[218:219], v5
	v_cvt_pk_f32_fp8_sdwa v[220:221], v5 src0_sel:WORD_1
	v_pk_fma_f32 v[202:203], v[150:151], v[218:219], v[202:203] op_sel:[1,0,0]
	v_pk_fma_f32 v[204:205], v[150:151], v[220:221], v[204:205] op_sel:[1,0,0]
	v_cvt_pk_f32_fp8_e32 v[214:215], v6
	v_cvt_pk_f32_fp8_sdwa v[216:217], v6 src0_sel:WORD_1
	v_pk_fma_f32 v[206:207], v[150:151], v[214:215], v[206:207] op_sel:[1,0,0]
	v_pk_fma_f32 v[208:209], v[150:151], v[216:217], v[208:209] op_sel:[1,0,0]
	v_cvt_pk_f32_fp8_e32 v[218:219], v7
	v_cvt_pk_f32_fp8_sdwa v[220:221], v7 src0_sel:WORD_1
	v_pk_fma_f32 v[210:211], v[150:151], v[218:219], v[210:211] op_sel:[1,0,0]
	v_pk_fma_f32 v[212:213], v[150:151], v[220:221], v[212:213] op_sel:[1,0,0]
	s_waitcnt vmcnt(29)
	v_cvt_pk_f32_fp8_e32 v[214:215], v8
	v_cvt_pk_f32_fp8_sdwa v[216:217], v8 src0_sel:WORD_1
	v_pk_fma_f32 v[198:199], v[152:153], v[214:215], v[198:199] op_sel_hi:[0,1,1]
	v_pk_fma_f32 v[200:201], v[152:153], v[216:217], v[200:201] op_sel_hi:[0,1,1]
	v_cvt_pk_f32_fp8_e32 v[218:219], v9
	v_cvt_pk_f32_fp8_sdwa v[220:221], v9 src0_sel:WORD_1
	v_pk_fma_f32 v[202:203], v[152:153], v[218:219], v[202:203] op_sel_hi:[0,1,1]
	v_pk_fma_f32 v[204:205], v[152:153], v[220:221], v[204:205] op_sel_hi:[0,1,1]
	v_cvt_pk_f32_fp8_e32 v[214:215], v10
	v_cvt_pk_f32_fp8_sdwa v[216:217], v10 src0_sel:WORD_1
	v_pk_fma_f32 v[206:207], v[152:153], v[214:215], v[206:207] op_sel_hi:[0,1,1]
	v_pk_fma_f32 v[208:209], v[152:153], v[216:217], v[208:209] op_sel_hi:[0,1,1]
	v_cvt_pk_f32_fp8_e32 v[218:219], v11
	v_cvt_pk_f32_fp8_sdwa v[220:221], v11 src0_sel:WORD_1
	v_pk_fma_f32 v[210:211], v[152:153], v[218:219], v[210:211] op_sel_hi:[0,1,1]
	v_pk_fma_f32 v[212:213], v[152:153], v[220:221], v[212:213] op_sel_hi:[0,1,1]
	s_waitcnt vmcnt(28)
	v_cvt_pk_f32_fp8_e32 v[214:215], v12
	v_cvt_pk_f32_fp8_sdwa v[216:217], v12 src0_sel:WORD_1
	v_pk_fma_f32 v[198:199], v[152:153], v[214:215], v[198:199] op_sel:[1,0,0]
	v_pk_fma_f32 v[200:201], v[152:153], v[216:217], v[200:201] op_sel:[1,0,0]
	v_cvt_pk_f32_fp8_e32 v[218:219], v13
	v_cvt_pk_f32_fp8_sdwa v[220:221], v13 src0_sel:WORD_1
	v_pk_fma_f32 v[202:203], v[152:153], v[218:219], v[202:203] op_sel:[1,0,0]
	v_pk_fma_f32 v[204:205], v[152:153], v[220:221], v[204:205] op_sel:[1,0,0]
	v_cvt_pk_f32_fp8_e32 v[214:215], v14
	v_cvt_pk_f32_fp8_sdwa v[216:217], v14 src0_sel:WORD_1
	v_pk_fma_f32 v[206:207], v[152:153], v[214:215], v[206:207] op_sel:[1,0,0]
	v_pk_fma_f32 v[208:209], v[152:153], v[216:217], v[208:209] op_sel:[1,0,0]
	v_cvt_pk_f32_fp8_e32 v[218:219], v15
	v_cvt_pk_f32_fp8_sdwa v[220:221], v15 src0_sel:WORD_1
	v_pk_fma_f32 v[210:211], v[152:153], v[218:219], v[210:211] op_sel:[1,0,0]
	v_pk_fma_f32 v[212:213], v[152:153], v[220:221], v[212:213] op_sel:[1,0,0]
	ds_read_b128 v[150:153], v139 offset:0
	s_waitcnt vmcnt(27)
	v_cvt_pk_f32_fp8_e32 v[214:215], v16
	v_cvt_pk_f32_fp8_sdwa v[216:217], v16 src0_sel:WORD_1
	v_pk_fma_f32 v[198:199], v[154:155], v[214:215], v[198:199] op_sel_hi:[0,1,1]
	v_pk_fma_f32 v[200:201], v[154:155], v[216:217], v[200:201] op_sel_hi:[0,1,1]
	v_cvt_pk_f32_fp8_e32 v[218:219], v17
	v_cvt_pk_f32_fp8_sdwa v[220:221], v17 src0_sel:WORD_1
	v_pk_fma_f32 v[202:203], v[154:155], v[218:219], v[202:203] op_sel_hi:[0,1,1]
	v_pk_fma_f32 v[204:205], v[154:155], v[220:221], v[204:205] op_sel_hi:[0,1,1]
	v_cvt_pk_f32_fp8_e32 v[214:215], v18
	v_cvt_pk_f32_fp8_sdwa v[216:217], v18 src0_sel:WORD_1
	v_pk_fma_f32 v[206:207], v[154:155], v[214:215], v[206:207] op_sel_hi:[0,1,1]
	v_pk_fma_f32 v[208:209], v[154:155], v[216:217], v[208:209] op_sel_hi:[0,1,1]
	v_cvt_pk_f32_fp8_e32 v[218:219], v19
	v_cvt_pk_f32_fp8_sdwa v[220:221], v19 src0_sel:WORD_1
	v_pk_fma_f32 v[210:211], v[154:155], v[218:219], v[210:211] op_sel_hi:[0,1,1]
	v_pk_fma_f32 v[212:213], v[154:155], v[220:221], v[212:213] op_sel_hi:[0,1,1]
	s_waitcnt vmcnt(26)
	v_cvt_pk_f32_fp8_e32 v[214:215], v20
	v_cvt_pk_f32_fp8_sdwa v[216:217], v20 src0_sel:WORD_1
	v_pk_fma_f32 v[198:199], v[154:155], v[214:215], v[198:199] op_sel:[1,0,0]
	v_pk_fma_f32 v[200:201], v[154:155], v[216:217], v[200:201] op_sel:[1,0,0]
	v_cvt_pk_f32_fp8_e32 v[218:219], v21
	v_cvt_pk_f32_fp8_sdwa v[220:221], v21 src0_sel:WORD_1
	v_pk_fma_f32 v[202:203], v[154:155], v[218:219], v[202:203] op_sel:[1,0,0]
	v_pk_fma_f32 v[204:205], v[154:155], v[220:221], v[204:205] op_sel:[1,0,0]
	v_cvt_pk_f32_fp8_e32 v[214:215], v22
	v_cvt_pk_f32_fp8_sdwa v[216:217], v22 src0_sel:WORD_1
	v_pk_fma_f32 v[206:207], v[154:155], v[214:215], v[206:207] op_sel:[1,0,0]
	v_pk_fma_f32 v[208:209], v[154:155], v[216:217], v[208:209] op_sel:[1,0,0]
	v_cvt_pk_f32_fp8_e32 v[218:219], v23
	v_cvt_pk_f32_fp8_sdwa v[220:221], v23 src0_sel:WORD_1
	v_pk_fma_f32 v[210:211], v[154:155], v[218:219], v[210:211] op_sel:[1,0,0]
	v_pk_fma_f32 v[212:213], v[154:155], v[220:221], v[212:213] op_sel:[1,0,0]
	s_waitcnt lgkmcnt(0)
	v_lshl_add_u32 v150, v150, 8, v138
	v_lshl_add_u32 v151, v151, 8, v138
	v_lshl_add_u32 v152, v152, 8, v138
	v_lshl_add_u32 v153, v153, 8, v138
	buffer_load_dwordx4 v[0:3], v150, s[16:19], s26 offen
	buffer_load_dwordx4 v[4:7], v151, s[16:19], s26 offen
	buffer_load_dwordx4 v[8:11], v152, s[16:19], s26 offen
	buffer_load_dwordx4 v[12:15], v153, s[16:19], s26 offen
	s_waitcnt vmcnt(29)
; #define LAS __attribute__((address_space(3)))
; __device__ __forceinline__ void kv8_issue(u32x4 (&buf)[8], __amdgpu_buffer_rsrc_t rs, int voff  , int sbase  , const int (&iv)[4], int b) {
;     const int jj = b >> 3, l0 = (b & 7) * 8;
;     const int ivb = (jj == 0) ? iv[0] : (jj == 1) ? iv[1] : (jj == 2) ? iv[2] : iv[3];
; #pragma unroll
;     for (int u = 0; u < 8; ++u) { const int si = __builtin_amdgcn_readlane(ivb, l0 + u); buf[u] = __builtin_amdgcn_raw_buffer_load_b128(rs, voff, si * 2048 + sbase, KV8_AUX); }
; }
; __device__ __forceinline__ void kv8_pv(const u32x4 (&buf)[8], f32x2v (&o2)[8], const LAS float* srow, int b) {
;     const LAS f32x4* p4 = (const LAS f32x4*)(srow + b * 8);
;     const f32x4 p0 = p4[0], p1 = p4[1];
;     const float p[8] = {p0.x, p0.y, p0.z, p0.w, p1.x, p1.y, p1.z, p1.w};
; #pragma unroll
;     for (int u = 0; u < 8; ++u) {
;         const u32x4 v = buf[u]; const f32x2v pp = {p[u], p[u]};
;         o2[0] = __builtin_elementwise_fma(pp, __builtin_amdgcn_cvt_pk_f32_fp8(v.x, false), o2[0]); o2[1] = __builtin_elementwise_fma(pp, __builtin_amdgcn_cvt_pk_f32_fp8(v.x, true), o2[1]);
;         o2[2] = __builtin_elementwise_fma(pp, __builtin_amdgcn_cvt_pk_f32_fp8(v.y, false), o2[2]); o2[3] = __builtin_elementwise_fma(pp, __builtin_amdgcn_cvt_pk_f32_fp8(v.y, true), o2[3]);
;         o2[4] = __builtin_elementwise_fma(pp, __builtin_amdgcn_cvt_pk_f32_fp8(v.z, false), o2[4]); o2[5] = __builtin_elementwise_fma(pp, __builtin_amdgcn_cvt_pk_f32_fp8(v.z, true), o2[5]);
;         o2[6] = __builtin_elementwise_fma(pp, __builtin_amdgcn_cvt_pk_f32_fp8(v.w, false), o2[6]); o2[7] = __builtin_elementwise_fma(pp, __builtin_amdgcn_cvt_pk_f32_fp8(v.w, true), o2[7]);
;     }
	v_cvt_pk_f32_fp8_e32 v[214:215], v24
	v_cvt_pk_f32_fp8_sdwa v[216:217], v24 src0_sel:WORD_1
	v_pk_fma_f32 v[198:199], v[156:157], v[214:215], v[198:199] op_sel_hi:[0,1,1]
	v_pk_fma_f32 v[200:201], v[156:157], v[216:217], v[200:201] op_sel_hi:[0,1,1]
	v_cvt_pk_f32_fp8_e32 v[218:219], v25
	v_cvt_pk_f32_fp8_sdwa v[220:221], v25 src0_sel:WORD_1
	v_pk_fma_f32 v[202:203], v[156:157], v[218:219], v[202:203] op_sel_hi:[0,1,1]
	v_pk_fma_f32 v[204:205], v[156:157], v[220:221], v[204:205] op_sel_hi:[0,1,1]
	v_cvt_pk_f32_fp8_e32 v[214:215], v26
	v_cvt_pk_f32_fp8_sdwa v[216:217], v26 src0_sel:WORD_1
	v_pk_fma_f32 v[206:207], v[156:157], v[214:215], v[206:207] op_sel_hi:[0,1,1]
	v_pk_fma_f32 v[208:209], v[156:157], v[216:217], v[208:209] op_sel_hi:[0,1,1]
	v_cvt_pk_f32_fp8_e32 v[218:219], v27
	v_cvt_pk_f32_fp8_sdwa v[220:221], v27 src0_sel:WORD_1
	v_pk_fma_f32 v[210:211], v[156:157], v[218:219], v[210:211] op_sel_hi:[0,1,1]
	v_pk_fma_f32 v[212:213], v[156:157], v[220:221], v[212:213] op_sel_hi:[0,1,1]
	s_waitcnt vmcnt(28)
	v_cvt_pk_f32_fp8_e32 v[214:215], v28
	v_cvt_pk_f32_fp8_sdwa v[216:217], v28 src0_sel:WORD_1
	v_pk_fma_f32 v[198:199], v[156:157], v[214:215], v[198:199] op_sel:[1,0,0]
	v_pk_fma_f32 v[200:201], v[156:157], v[216:217], v[200:201] op_sel:[1,0,0]
	v_cvt_pk_f32_fp8_e32 v[218:219], v29
	v_cvt_pk_f32_fp8_sdwa v[220:221], v29 src0_sel:WORD_1
	v_pk_fma_f32 v[202:203], v[156:157], v[218:219], v[202:203] op_sel:[1,0,0]
	v_pk_fma_f32 v[204:205], v[156:157], v[220:221], v[204:205] op_sel:[1,0,0]
	v_cvt_pk_f32_fp8_e32 v[214:215], v30
	v_cvt_pk_f32_fp8_sdwa v[216:217], v30 src0_sel:WORD_1
	v_pk_fma_f32 v[206:207], v[156:157], v[214:215], v[206:207] op_sel:[1,0,0]
	v_pk_fma_f32 v[208:209], v[156:157], v[216:217], v[208:209] op_sel:[1,0,0]
	v_cvt_pk_f32_fp8_e32 v[218:219], v31
	v_cvt_pk_f32_fp8_sdwa v[220:221], v31 src0_sel:WORD_1
	v_pk_fma_f32 v[210:211], v[156:157], v[218:219], v[210:211] op_sel:[1,0,0]
	v_pk_fma_f32 v[212:213], v[156:157], v[220:221], v[212:213] op_sel:[1,0,0]
	ds_read_b128 v[154:157], v139 offset:16
	s_waitcnt vmcnt(27)
	v_cvt_pk_f32_fp8_e32 v[214:215], v32
	v_cvt_pk_f32_fp8_sdwa v[216:217], v32 src0_sel:WORD_1
	v_pk_fma_f32 v[198:199], v[158:159], v[214:215], v[198:199] op_sel_hi:[0,1,1]
	v_pk_fma_f32 v[200:201], v[158:159], v[216:217], v[200:201] op_sel_hi:[0,1,1]
	v_cvt_pk_f32_fp8_e32 v[218:219], v33
	v_cvt_pk_f32_fp8_sdwa v[220:221], v33 src0_sel:WORD_1
	v_pk_fma_f32 v[202:203], v[158:159], v[218:219], v[202:203] op_sel_hi:[0,1,1]
	v_pk_fma_f32 v[204:205], v[158:159], v[220:221], v[204:205] op_sel_hi:[0,1,1]
	v_cvt_pk_f32_fp8_e32 v[214:215], v34
	v_cvt_pk_f32_fp8_sdwa v[216:217], v34 src0_sel:WORD_1
	v_pk_fma_f32 v[206:207], v[158:159], v[214:215], v[206:207] op_sel_hi:[0,1,1]
	v_pk_fma_f32 v[208:209], v[158:159], v[216:217], v[208:209] op_sel_hi:[0,1,1]
	v_cvt_pk_f32_fp8_e32 v[218:219], v35
	v_cvt_pk_f32_fp8_sdwa v[220:221], v35 src0_sel:WORD_1
	v_pk_fma_f32 v[210:211], v[158:159], v[218:219], v[210:211] op_sel_hi:[0,1,1]
	v_pk_fma_f32 v[212:213], v[158:159], v[220:221], v[212:213] op_sel_hi:[0,1,1]
	s_waitcnt vmcnt(26)
	v_cvt_pk_f32_fp8_e32 v[214:215], v36
	v_cvt_pk_f32_fp8_sdwa v[216:217], v36 src0_sel:WORD_1
	v_pk_fma_f32 v[198:199], v[158:159], v[214:215], v[198:199] op_sel:[1,0,0]
	v_pk_fma_f32 v[200:201], v[158:159], v[216:217], v[200:201] op_sel:[1,0,0]
	v_cvt_pk_f32_fp8_e32 v[218:219], v37
	v_cvt_pk_f32_fp8_sdwa v[220:221], v37 src0_sel:WORD_1
	v_pk_fma_f32 v[202:203], v[158:159], v[218:219], v[202:203] op_sel:[1,0,0]
	v_pk_fma_f32 v[204:205], v[158:159], v[220:221], v[204:205] op_sel:[1,0,0]
	v_cvt_pk_f32_fp8_e32 v[214:215], v38
	v_cvt_pk_f32_fp8_sdwa v[216:217], v38 src0_sel:WORD_1
	v_pk_fma_f32 v[206:207], v[158:159], v[214:215], v[206:207] op_sel:[1,0,0]
	v_pk_fma_f32 v[208:209], v[158:159], v[216:217], v[208:209] op_sel:[1,0,0]
	v_cvt_pk_f32_fp8_e32 v[218:219], v39
	v_cvt_pk_f32_fp8_sdwa v[220:221], v39 src0_sel:WORD_1
	v_pk_fma_f32 v[210:211], v[158:159], v[218:219], v[210:211] op_sel:[1,0,0]
	v_pk_fma_f32 v[212:213], v[158:159], v[220:221], v[212:213] op_sel:[1,0,0]
	s_waitcnt lgkmcnt(0)
	v_lshl_add_u32 v154, v154, 8, v138
	v_lshl_add_u32 v155, v155, 8, v138
	v_lshl_add_u32 v156, v156, 8, v138
	v_lshl_add_u32 v157, v157, 8, v138
	buffer_load_dwordx4 v[16:19], v154, s[16:19], s26 offen
	buffer_load_dwordx4 v[20:23], v155, s[16:19], s26 offen
	buffer_load_dwordx4 v[24:27], v156, s[16:19], s26 offen
	buffer_load_dwordx4 v[28:31], v157, s[16:19], s26 offen
	s_waitcnt vmcnt(29)
	v_cvt_pk_f32_fp8_e32 v[214:215], v40
	v_cvt_pk_f32_fp8_sdwa v[216:217], v40 src0_sel:WORD_1
	v_pk_fma_f32 v[198:199], v[160:161], v[214:215], v[198:199] op_sel_hi:[0,1,1]
	v_pk_fma_f32 v[200:201], v[160:161], v[216:217], v[200:201] op_sel_hi:[0,1,1]
	v_cvt_pk_f32_fp8_e32 v[218:219], v41
	v_cvt_pk_f32_fp8_sdwa v[220:221], v41 src0_sel:WORD_1
	v_pk_fma_f32 v[202:203], v[160:161], v[218:219], v[202:203] op_sel_hi:[0,1,1]
	v_pk_fma_f32 v[204:205], v[160:161], v[220:221], v[204:205] op_sel_hi:[0,1,1]
	v_cvt_pk_f32_fp8_e32 v[214:215], v42
	v_cvt_pk_f32_fp8_sdwa v[216:217], v42 src0_sel:WORD_1
	v_pk_fma_f32 v[206:207], v[160:161], v[214:215], v[206:207] op_sel_hi:[0,1,1]
	v_pk_fma_f32 v[208:209], v[160:161], v[216:217], v[208:209] op_sel_hi:[0,1,1]
	v_cvt_pk_f32_fp8_e32 v[218:219], v43
	v_cvt_pk_f32_fp8_sdwa v[220:221], v43 src0_sel:WORD_1
	v_pk_fma_f32 v[210:211], v[160:161], v[218:219], v[210:211] op_sel_hi:[0,1,1]
	v_pk_fma_f32 v[212:213], v[160:161], v[220:221], v[212:213] op_sel_hi:[0,1,1]
	s_waitcnt vmcnt(28)
; #define LAS __attribute__((address_space(3)))
; __device__ __forceinline__ void kv8_issue(u32x4 (&buf)[8], __amdgpu_buffer_rsrc_t rs, int voff  , int sbase  , const int (&iv)[4], int b) {
;     const int jj = b >> 3, l0 = (b & 7) * 8;
;     const int ivb = (jj == 0) ? iv[0] : (jj == 1) ? iv[1] : (jj == 2) ? iv[2] : iv[3];
; #pragma unroll
;     for (int u = 0; u < 8; ++u) { const int si = __builtin_amdgcn_readlane(ivb, l0 + u); buf[u] = __builtin_amdgcn_raw_buffer_load_b128(rs, voff, si * 2048 + sbase, KV8_AUX); }
; }
; __device__ __forceinline__ void kv8_pv(const u32x4 (&buf)[8], f32x2v (&o2)[8], const LAS float* srow, int b) {
;     const LAS f32x4* p4 = (const LAS f32x4*)(srow + b * 8);
;     const f32x4 p0 = p4[0], p1 = p4[1];
;     const float p[8] = {p0.x, p0.y, p0.z, p0.w, p1.x, p1.y, p1.z, p1.w};
; #pragma unroll
;     for (int u = 0; u < 8; ++u) {
;         const u32x4 v = buf[u]; const f32x2v pp = {p[u], p[u]};
;         o2[0] = __builtin_elementwise_fma(pp, __builtin_amdgcn_cvt_pk_f32_fp8(v.x, false), o2[0]); o2[1] = __builtin_elementwise_fma(pp, __builtin_amdgcn_cvt_pk_f32_fp8(v.x, true), o2[1]);
;         o2[2] = __builtin_elementwise_fma(pp, __builtin_amdgcn_cvt_pk_f32_fp8(v.y, false), o2[2]); o2[3] = __builtin_elementwise_fma(pp, __builtin_amdgcn_cvt_pk_f32_fp8(v.y, true), o2[3]);
;         o2[4] = __builtin_elementwise_fma(pp, __builtin_amdgcn_cvt_pk_f32_fp8(v.z, false), o2[4]); o2[5] = __builtin_elementwise_fma(pp, __builtin_amdgcn_cvt_pk_f32_fp8(v.z, true), o2[5]);
;         o2[6] = __builtin_elementwise_fma(pp, __builtin_amdgcn_cvt_pk_f32_fp8(v.w, false), o2[6]); o2[7] = __builtin_elementwise_fma(pp, __builtin_amdgcn_cvt_pk_f32_fp8(v.w, true), o2[7]);
;     }
	v_cvt_pk_f32_fp8_e32 v[214:215], v44
	v_cvt_pk_f32_fp8_sdwa v[216:217], v44 src0_sel:WORD_1
	v_pk_fma_f32 v[198:199], v[160:161], v[214:215], v[198:199] op_sel:[1,0,0]
	v_pk_fma_f32 v[200:201], v[160:161], v[216:217], v[200:201] op_sel:[1,0,0]
	v_cvt_pk_f32_fp8_e32 v[218:219], v45
	v_cvt_pk_f32_fp8_sdwa v[220:221], v45 src0_sel:WORD_1
	v_pk_fma_f32 v[202:203], v[160:161], v[218:219], v[202:203] op_sel:[1,0,0]
	v_pk_fma_f32 v[204:205], v[160:161], v[220:221], v[204:205] op_sel:[1,0,0]
	v_cvt_pk_f32_fp8_e32 v[214:215], v46
	v_cvt_pk_f32_fp8_sdwa v[216:217], v46 src0_sel:WORD_1
	v_pk_fma_f32 v[206:207], v[160:161], v[214:215], v[206:207] op_sel:[1,0,0]
	v_pk_fma_f32 v[208:209], v[160:161], v[216:217], v[208:209] op_sel:[1,0,0]
	v_cvt_pk_f32_fp8_e32 v[218:219], v47
	v_cvt_pk_f32_fp8_sdwa v[220:221], v47 src0_sel:WORD_1
	v_pk_fma_f32 v[210:211], v[160:161], v[218:219], v[210:211] op_sel:[1,0,0]
	v_pk_fma_f32 v[212:213], v[160:161], v[220:221], v[212:213] op_sel:[1,0,0]
	ds_read_b128 v[158:161], v139 offset:32
	s_waitcnt vmcnt(27)
	v_cvt_pk_f32_fp8_e32 v[214:215], v48
	v_cvt_pk_f32_fp8_sdwa v[216:217], v48 src0_sel:WORD_1
	v_pk_fma_f32 v[198:199], v[162:163], v[214:215], v[198:199] op_sel_hi:[0,1,1]
	v_pk_fma_f32 v[200:201], v[162:163], v[216:217], v[200:201] op_sel_hi:[0,1,1]
	v_cvt_pk_f32_fp8_e32 v[218:219], v49
	v_cvt_pk_f32_fp8_sdwa v[220:221], v49 src0_sel:WORD_1
	v_pk_fma_f32 v[202:203], v[162:163], v[218:219], v[202:203] op_sel_hi:[0,1,1]
	v_pk_fma_f32 v[204:205], v[162:163], v[220:221], v[204:205] op_sel_hi:[0,1,1]
	v_cvt_pk_f32_fp8_e32 v[214:215], v50
	v_cvt_pk_f32_fp8_sdwa v[216:217], v50 src0_sel:WORD_1
	v_pk_fma_f32 v[206:207], v[162:163], v[214:215], v[206:207] op_sel_hi:[0,1,1]
	v_pk_fma_f32 v[208:209], v[162:163], v[216:217], v[208:209] op_sel_hi:[0,1,1]
	v_cvt_pk_f32_fp8_e32 v[218:219], v51
	v_cvt_pk_f32_fp8_sdwa v[220:221], v51 src0_sel:WORD_1
	v_pk_fma_f32 v[210:211], v[162:163], v[218:219], v[210:211] op_sel_hi:[0,1,1]
	v_pk_fma_f32 v[212:213], v[162:163], v[220:221], v[212:213] op_sel_hi:[0,1,1]
	s_waitcnt vmcnt(26)
	v_cvt_pk_f32_fp8_e32 v[214:215], v52
	v_cvt_pk_f32_fp8_sdwa v[216:217], v52 src0_sel:WORD_1
	v_pk_fma_f32 v[198:199], v[162:163], v[214:215], v[198:199] op_sel:[1,0,0]
	v_pk_fma_f32 v[200:201], v[162:163], v[216:217], v[200:201] op_sel:[1,0,0]
	v_cvt_pk_f32_fp8_e32 v[218:219], v53
	v_cvt_pk_f32_fp8_sdwa v[220:221], v53 src0_sel:WORD_1
	v_pk_fma_f32 v[202:203], v[162:163], v[218:219], v[202:203] op_sel:[1,0,0]
	v_pk_fma_f32 v[204:205], v[162:163], v[220:221], v[204:205] op_sel:[1,0,0]
	v_cvt_pk_f32_fp8_e32 v[214:215], v54
	v_cvt_pk_f32_fp8_sdwa v[216:217], v54 src0_sel:WORD_1
	v_pk_fma_f32 v[206:207], v[162:163], v[214:215], v[206:207] op_sel:[1,0,0]
	v_pk_fma_f32 v[208:209], v[162:163], v[216:217], v[208:209] op_sel:[1,0,0]
	v_cvt_pk_f32_fp8_e32 v[218:219], v55
	v_cvt_pk_f32_fp8_sdwa v[220:221], v55 src0_sel:WORD_1
	v_pk_fma_f32 v[210:211], v[162:163], v[218:219], v[210:211] op_sel:[1,0,0]
	v_pk_fma_f32 v[212:213], v[162:163], v[220:221], v[212:213] op_sel:[1,0,0]
	s_waitcnt lgkmcnt(0)
	v_lshl_add_u32 v158, v158, 8, v138
	v_lshl_add_u32 v159, v159, 8, v138
	v_lshl_add_u32 v160, v160, 8, v138
	v_lshl_add_u32 v161, v161, 8, v138
	buffer_load_dwordx4 v[32:35], v158, s[16:19], s26 offen
	buffer_load_dwordx4 v[36:39], v159, s[16:19], s26 offen
	buffer_load_dwordx4 v[40:43], v160, s[16:19], s26 offen
	buffer_load_dwordx4 v[44:47], v161, s[16:19], s26 offen
	s_waitcnt vmcnt(29)
	v_cvt_pk_f32_fp8_e32 v[214:215], v56
	v_cvt_pk_f32_fp8_sdwa v[216:217], v56 src0_sel:WORD_1
	v_pk_fma_f32 v[198:199], v[164:165], v[214:215], v[198:199] op_sel_hi:[0,1,1]
	v_pk_fma_f32 v[200:201], v[164:165], v[216:217], v[200:201] op_sel_hi:[0,1,1]
	v_cvt_pk_f32_fp8_e32 v[218:219], v57
	v_cvt_pk_f32_fp8_sdwa v[220:221], v57 src0_sel:WORD_1
	v_pk_fma_f32 v[202:203], v[164:165], v[218:219], v[202:203] op_sel_hi:[0,1,1]
	v_pk_fma_f32 v[204:205], v[164:165], v[220:221], v[204:205] op_sel_hi:[0,1,1]
	v_cvt_pk_f32_fp8_e32 v[214:215], v58
	v_cvt_pk_f32_fp8_sdwa v[216:217], v58 src0_sel:WORD_1
	v_pk_fma_f32 v[206:207], v[164:165], v[214:215], v[206:207] op_sel_hi:[0,1,1]
	v_pk_fma_f32 v[208:209], v[164:165], v[216:217], v[208:209] op_sel_hi:[0,1,1]
	v_cvt_pk_f32_fp8_e32 v[218:219], v59
	v_cvt_pk_f32_fp8_sdwa v[220:221], v59 src0_sel:WORD_1
	v_pk_fma_f32 v[210:211], v[164:165], v[218:219], v[210:211] op_sel_hi:[0,1,1]
	v_pk_fma_f32 v[212:213], v[164:165], v[220:221], v[212:213] op_sel_hi:[0,1,1]
	s_waitcnt vmcnt(28)
	v_cvt_pk_f32_fp8_e32 v[214:215], v60
	v_cvt_pk_f32_fp8_sdwa v[216:217], v60 src0_sel:WORD_1
	v_pk_fma_f32 v[198:199], v[164:165], v[214:215], v[198:199] op_sel:[1,0,0]
	v_pk_fma_f32 v[200:201], v[164:165], v[216:217], v[200:201] op_sel:[1,0,0]
	v_cvt_pk_f32_fp8_e32 v[218:219], v61
	v_cvt_pk_f32_fp8_sdwa v[220:221], v61 src0_sel:WORD_1
	v_pk_fma_f32 v[202:203], v[164:165], v[218:219], v[202:203] op_sel:[1,0,0]
	v_pk_fma_f32 v[204:205], v[164:165], v[220:221], v[204:205] op_sel:[1,0,0]
	v_cvt_pk_f32_fp8_e32 v[214:215], v62
	v_cvt_pk_f32_fp8_sdwa v[216:217], v62 src0_sel:WORD_1
	v_pk_fma_f32 v[206:207], v[164:165], v[214:215], v[206:207] op_sel:[1,0,0]
	v_pk_fma_f32 v[208:209], v[164:165], v[216:217], v[208:209] op_sel:[1,0,0]
	v_cvt_pk_f32_fp8_e32 v[218:219], v63
	v_cvt_pk_f32_fp8_sdwa v[220:221], v63 src0_sel:WORD_1
	v_pk_fma_f32 v[210:211], v[164:165], v[218:219], v[210:211] op_sel:[1,0,0]
	v_pk_fma_f32 v[212:213], v[164:165], v[220:221], v[212:213] op_sel:[1,0,0]
	ds_read_b128 v[162:165], v139 offset:48
	s_waitcnt vmcnt(27)
; #define LAS __attribute__((address_space(3)))
; __device__ __forceinline__ void kv8_issue(u32x4 (&buf)[8], __amdgpu_buffer_rsrc_t rs, int voff  , int sbase  , const int (&iv)[4], int b) {
;     const int jj = b >> 3, l0 = (b & 7) * 8;
;     const int ivb = (jj == 0) ? iv[0] : (jj == 1) ? iv[1] : (jj == 2) ? iv[2] : iv[3];
; #pragma unroll
;     for (int u = 0; u < 8; ++u) { const int si = __builtin_amdgcn_readlane(ivb, l0 + u); buf[u] = __builtin_amdgcn_raw_buffer_load_b128(rs, voff, si * 2048 + sbase, KV8_AUX); }
; }
; __device__ __forceinline__ void kv8_pv(const u32x4 (&buf)[8], f32x2v (&o2)[8], const LAS float* srow, int b) {
;     const LAS f32x4* p4 = (const LAS f32x4*)(srow + b * 8);
;     const f32x4 p0 = p4[0], p1 = p4[1];
;     const float p[8] = {p0.x, p0.y, p0.z, p0.w, p1.x, p1.y, p1.z, p1.w};
; #pragma unroll
;     for (int u = 0; u < 8; ++u) {
;         const u32x4 v = buf[u]; const f32x2v pp = {p[u], p[u]};
;         o2[0] = __builtin_elementwise_fma(pp, __builtin_amdgcn_cvt_pk_f32_fp8(v.x, false), o2[0]); o2[1] = __builtin_elementwise_fma(pp, __builtin_amdgcn_cvt_pk_f32_fp8(v.x, true), o2[1]);
;         o2[2] = __builtin_elementwise_fma(pp, __builtin_amdgcn_cvt_pk_f32_fp8(v.y, false), o2[2]); o2[3] = __builtin_elementwise_fma(pp, __builtin_amdgcn_cvt_pk_f32_fp8(v.y, true), o2[3]);
;         o2[4] = __builtin_elementwise_fma(pp, __builtin_amdgcn_cvt_pk_f32_fp8(v.z, false), o2[4]); o2[5] = __builtin_elementwise_fma(pp, __builtin_amdgcn_cvt_pk_f32_fp8(v.z, true), o2[5]);
;         o2[6] = __builtin_elementwise_fma(pp, __builtin_amdgcn_cvt_pk_f32_fp8(v.w, false), o2[6]); o2[7] = __builtin_elementwise_fma(pp, __builtin_amdgcn_cvt_pk_f32_fp8(v.w, true), o2[7]);
;     }
	v_cvt_pk_f32_fp8_e32 v[214:215], v64
	v_cvt_pk_f32_fp8_sdwa v[216:217], v64 src0_sel:WORD_1
	v_pk_fma_f32 v[198:199], v[166:167], v[214:215], v[198:199] op_sel_hi:[0,1,1]
	v_pk_fma_f32 v[200:201], v[166:167], v[216:217], v[200:201] op_sel_hi:[0,1,1]
	v_cvt_pk_f32_fp8_e32 v[218:219], v65
	v_cvt_pk_f32_fp8_sdwa v[220:221], v65 src0_sel:WORD_1
	v_pk_fma_f32 v[202:203], v[166:167], v[218:219], v[202:203] op_sel_hi:[0,1,1]
	v_pk_fma_f32 v[204:205], v[166:167], v[220:221], v[204:205] op_sel_hi:[0,1,1]
	v_cvt_pk_f32_fp8_e32 v[214:215], v66
	v_cvt_pk_f32_fp8_sdwa v[216:217], v66 src0_sel:WORD_1
	v_pk_fma_f32 v[206:207], v[166:167], v[214:215], v[206:207] op_sel_hi:[0,1,1]
	v_pk_fma_f32 v[208:209], v[166:167], v[216:217], v[208:209] op_sel_hi:[0,1,1]
	v_cvt_pk_f32_fp8_e32 v[218:219], v67
	v_cvt_pk_f32_fp8_sdwa v[220:221], v67 src0_sel:WORD_1
	v_pk_fma_f32 v[210:211], v[166:167], v[218:219], v[210:211] op_sel_hi:[0,1,1]
	v_pk_fma_f32 v[212:213], v[166:167], v[220:221], v[212:213] op_sel_hi:[0,1,1]
	s_waitcnt vmcnt(26)
	v_cvt_pk_f32_fp8_e32 v[214:215], v68
	v_cvt_pk_f32_fp8_sdwa v[216:217], v68 src0_sel:WORD_1
	v_pk_fma_f32 v[198:199], v[166:167], v[214:215], v[198:199] op_sel:[1,0,0]
	v_pk_fma_f32 v[200:201], v[166:167], v[216:217], v[200:201] op_sel:[1,0,0]
	v_cvt_pk_f32_fp8_e32 v[218:219], v69
	v_cvt_pk_f32_fp8_sdwa v[220:221], v69 src0_sel:WORD_1
	v_pk_fma_f32 v[202:203], v[166:167], v[218:219], v[202:203] op_sel:[1,0,0]
	v_pk_fma_f32 v[204:205], v[166:167], v[220:221], v[204:205] op_sel:[1,0,0]
	v_cvt_pk_f32_fp8_e32 v[214:215], v70
	v_cvt_pk_f32_fp8_sdwa v[216:217], v70 src0_sel:WORD_1
	v_pk_fma_f32 v[206:207], v[166:167], v[214:215], v[206:207] op_sel:[1,0,0]
	v_pk_fma_f32 v[208:209], v[166:167], v[216:217], v[208:209] op_sel:[1,0,0]
	v_cvt_pk_f32_fp8_e32 v[218:219], v71
	v_cvt_pk_f32_fp8_sdwa v[220:221], v71 src0_sel:WORD_1
	v_pk_fma_f32 v[210:211], v[166:167], v[218:219], v[210:211] op_sel:[1,0,0]
	v_pk_fma_f32 v[212:213], v[166:167], v[220:221], v[212:213] op_sel:[1,0,0]
	s_waitcnt lgkmcnt(0)
	v_lshl_add_u32 v162, v162, 8, v138
	v_lshl_add_u32 v163, v163, 8, v138
	v_lshl_add_u32 v164, v164, 8, v138
	v_lshl_add_u32 v165, v165, 8, v138
	buffer_load_dwordx4 v[48:51], v162, s[16:19], s26 offen
	buffer_load_dwordx4 v[52:55], v163, s[16:19], s26 offen
	buffer_load_dwordx4 v[56:59], v164, s[16:19], s26 offen
	buffer_load_dwordx4 v[60:63], v165, s[16:19], s26 offen
	s_waitcnt vmcnt(29)
	v_cvt_pk_f32_fp8_e32 v[214:215], v72
	v_cvt_pk_f32_fp8_sdwa v[216:217], v72 src0_sel:WORD_1
	v_pk_fma_f32 v[198:199], v[168:169], v[214:215], v[198:199] op_sel_hi:[0,1,1]
	v_pk_fma_f32 v[200:201], v[168:169], v[216:217], v[200:201] op_sel_hi:[0,1,1]
	v_cvt_pk_f32_fp8_e32 v[218:219], v73
	v_cvt_pk_f32_fp8_sdwa v[220:221], v73 src0_sel:WORD_1
	v_pk_fma_f32 v[202:203], v[168:169], v[218:219], v[202:203] op_sel_hi:[0,1,1]
	v_pk_fma_f32 v[204:205], v[168:169], v[220:221], v[204:205] op_sel_hi:[0,1,1]
	v_cvt_pk_f32_fp8_e32 v[214:215], v74
	v_cvt_pk_f32_fp8_sdwa v[216:217], v74 src0_sel:WORD_1
	v_pk_fma_f32 v[206:207], v[168:169], v[214:215], v[206:207] op_sel_hi:[0,1,1]
	v_pk_fma_f32 v[208:209], v[168:169], v[216:217], v[208:209] op_sel_hi:[0,1,1]
	v_cvt_pk_f32_fp8_e32 v[218:219], v75
	v_cvt_pk_f32_fp8_sdwa v[220:221], v75 src0_sel:WORD_1
	v_pk_fma_f32 v[210:211], v[168:169], v[218:219], v[210:211] op_sel_hi:[0,1,1]
	v_pk_fma_f32 v[212:213], v[168:169], v[220:221], v[212:213] op_sel_hi:[0,1,1]
	s_waitcnt vmcnt(28)
	v_cvt_pk_f32_fp8_e32 v[214:215], v76
	v_cvt_pk_f32_fp8_sdwa v[216:217], v76 src0_sel:WORD_1
	v_pk_fma_f32 v[198:199], v[168:169], v[214:215], v[198:199] op_sel:[1,0,0]
	v_pk_fma_f32 v[200:201], v[168:169], v[216:217], v[200:201] op_sel:[1,0,0]
	v_cvt_pk_f32_fp8_e32 v[218:219], v77
	v_cvt_pk_f32_fp8_sdwa v[220:221], v77 src0_sel:WORD_1
	v_pk_fma_f32 v[202:203], v[168:169], v[218:219], v[202:203] op_sel:[1,0,0]
	v_pk_fma_f32 v[204:205], v[168:169], v[220:221], v[204:205] op_sel:[1,0,0]
	v_cvt_pk_f32_fp8_e32 v[214:215], v78
	v_cvt_pk_f32_fp8_sdwa v[216:217], v78 src0_sel:WORD_1
	v_pk_fma_f32 v[206:207], v[168:169], v[214:215], v[206:207] op_sel:[1,0,0]
	v_pk_fma_f32 v[208:209], v[168:169], v[216:217], v[208:209] op_sel:[1,0,0]
	v_cvt_pk_f32_fp8_e32 v[218:219], v79
	v_cvt_pk_f32_fp8_sdwa v[220:221], v79 src0_sel:WORD_1
	v_pk_fma_f32 v[210:211], v[168:169], v[218:219], v[210:211] op_sel:[1,0,0]
	v_pk_fma_f32 v[212:213], v[168:169], v[220:221], v[212:213] op_sel:[1,0,0]
	ds_read_b128 v[166:169], v139 offset:64
	s_waitcnt vmcnt(27)
	v_cvt_pk_f32_fp8_e32 v[214:215], v80
	v_cvt_pk_f32_fp8_sdwa v[216:217], v80 src0_sel:WORD_1
	v_pk_fma_f32 v[198:199], v[170:171], v[214:215], v[198:199] op_sel_hi:[0,1,1]
	v_pk_fma_f32 v[200:201], v[170:171], v[216:217], v[200:201] op_sel_hi:[0,1,1]
	v_cvt_pk_f32_fp8_e32 v[218:219], v81
	v_cvt_pk_f32_fp8_sdwa v[220:221], v81 src0_sel:WORD_1
	v_pk_fma_f32 v[202:203], v[170:171], v[218:219], v[202:203] op_sel_hi:[0,1,1]
	v_pk_fma_f32 v[204:205], v[170:171], v[220:221], v[204:205] op_sel_hi:[0,1,1]
	v_cvt_pk_f32_fp8_e32 v[214:215], v82
	v_cvt_pk_f32_fp8_sdwa v[216:217], v82 src0_sel:WORD_1
	v_pk_fma_f32 v[206:207], v[170:171], v[214:215], v[206:207] op_sel_hi:[0,1,1]
	v_pk_fma_f32 v[208:209], v[170:171], v[216:217], v[208:209] op_sel_hi:[0,1,1]
	v_cvt_pk_f32_fp8_e32 v[218:219], v83
	v_cvt_pk_f32_fp8_sdwa v[220:221], v83 src0_sel:WORD_1
	v_pk_fma_f32 v[210:211], v[170:171], v[218:219], v[210:211] op_sel_hi:[0,1,1]
	v_pk_fma_f32 v[212:213], v[170:171], v[220:221], v[212:213] op_sel_hi:[0,1,1]
	s_waitcnt vmcnt(26)
; #define LAS __attribute__((address_space(3)))
; __device__ __forceinline__ void kv8_issue(u32x4 (&buf)[8], __amdgpu_buffer_rsrc_t rs, int voff  , int sbase  , const int (&iv)[4], int b) {
;     const int jj = b >> 3, l0 = (b & 7) * 8;
;     const int ivb = (jj == 0) ? iv[0] : (jj == 1) ? iv[1] : (jj == 2) ? iv[2] : iv[3];
; #pragma unroll
;     for (int u = 0; u < 8; ++u) { const int si = __builtin_amdgcn_readlane(ivb, l0 + u); buf[u] = __builtin_amdgcn_raw_buffer_load_b128(rs, voff, si * 2048 + sbase, KV8_AUX); }
; }
; __device__ __forceinline__ void kv8_pv(const u32x4 (&buf)[8], f32x2v (&o2)[8], const LAS float* srow, int b) {
;     const LAS f32x4* p4 = (const LAS f32x4*)(srow + b * 8);
;     const f32x4 p0 = p4[0], p1 = p4[1];
;     const float p[8] = {p0.x, p0.y, p0.z, p0.w, p1.x, p1.y, p1.z, p1.w};
; #pragma unroll
;     for (int u = 0; u < 8; ++u) {
;         const u32x4 v = buf[u]; const f32x2v pp = {p[u], p[u]};
;         o2[0] = __builtin_elementwise_fma(pp, __builtin_amdgcn_cvt_pk_f32_fp8(v.x, false), o2[0]); o2[1] = __builtin_elementwise_fma(pp, __builtin_amdgcn_cvt_pk_f32_fp8(v.x, true), o2[1]);
;         o2[2] = __builtin_elementwise_fma(pp, __builtin_amdgcn_cvt_pk_f32_fp8(v.y, false), o2[2]); o2[3] = __builtin_elementwise_fma(pp, __builtin_amdgcn_cvt_pk_f32_fp8(v.y, true), o2[3]);
;         o2[4] = __builtin_elementwise_fma(pp, __builtin_amdgcn_cvt_pk_f32_fp8(v.z, false), o2[4]); o2[5] = __builtin_elementwise_fma(pp, __builtin_amdgcn_cvt_pk_f32_fp8(v.z, true), o2[5]);
;         o2[6] = __builtin_elementwise_fma(pp, __builtin_amdgcn_cvt_pk_f32_fp8(v.w, false), o2[6]); o2[7] = __builtin_elementwise_fma(pp, __builtin_amdgcn_cvt_pk_f32_fp8(v.w, true), o2[7]);
;     }
	v_cvt_pk_f32_fp8_e32 v[214:215], v84
	v_cvt_pk_f32_fp8_sdwa v[216:217], v84 src0_sel:WORD_1
	v_pk_fma_f32 v[198:199], v[170:171], v[214:215], v[198:199] op_sel:[1,0,0]
	v_pk_fma_f32 v[200:201], v[170:171], v[216:217], v[200:201] op_sel:[1,0,0]
	v_cvt_pk_f32_fp8_e32 v[218:219], v85
	v_cvt_pk_f32_fp8_sdwa v[220:221], v85 src0_sel:WORD_1
	v_pk_fma_f32 v[202:203], v[170:171], v[218:219], v[202:203] op_sel:[1,0,0]
	v_pk_fma_f32 v[204:205], v[170:171], v[220:221], v[204:205] op_sel:[1,0,0]
	v_cvt_pk_f32_fp8_e32 v[214:215], v86
	v_cvt_pk_f32_fp8_sdwa v[216:217], v86 src0_sel:WORD_1
	v_pk_fma_f32 v[206:207], v[170:171], v[214:215], v[206:207] op_sel:[1,0,0]
	v_pk_fma_f32 v[208:209], v[170:171], v[216:217], v[208:209] op_sel:[1,0,0]
	v_cvt_pk_f32_fp8_e32 v[218:219], v87
	v_cvt_pk_f32_fp8_sdwa v[220:221], v87 src0_sel:WORD_1
	v_pk_fma_f32 v[210:211], v[170:171], v[218:219], v[210:211] op_sel:[1,0,0]
	v_pk_fma_f32 v[212:213], v[170:171], v[220:221], v[212:213] op_sel:[1,0,0]
	s_waitcnt lgkmcnt(0)
	v_lshl_add_u32 v166, v166, 8, v138
	v_lshl_add_u32 v167, v167, 8, v138
	v_lshl_add_u32 v168, v168, 8, v138
	v_lshl_add_u32 v169, v169, 8, v138
	buffer_load_dwordx4 v[64:67], v166, s[16:19], s26 offen
	buffer_load_dwordx4 v[68:71], v167, s[16:19], s26 offen
	buffer_load_dwordx4 v[72:75], v168, s[16:19], s26 offen
	buffer_load_dwordx4 v[76:79], v169, s[16:19], s26 offen
	s_waitcnt vmcnt(29)
	v_cvt_pk_f32_fp8_e32 v[214:215], v88
	v_cvt_pk_f32_fp8_sdwa v[216:217], v88 src0_sel:WORD_1
	v_pk_fma_f32 v[198:199], v[172:173], v[214:215], v[198:199] op_sel_hi:[0,1,1]
	v_pk_fma_f32 v[200:201], v[172:173], v[216:217], v[200:201] op_sel_hi:[0,1,1]
	v_cvt_pk_f32_fp8_e32 v[218:219], v89
	v_cvt_pk_f32_fp8_sdwa v[220:221], v89 src0_sel:WORD_1
	v_pk_fma_f32 v[202:203], v[172:173], v[218:219], v[202:203] op_sel_hi:[0,1,1]
	v_pk_fma_f32 v[204:205], v[172:173], v[220:221], v[204:205] op_sel_hi:[0,1,1]
	v_cvt_pk_f32_fp8_e32 v[214:215], v90
	v_cvt_pk_f32_fp8_sdwa v[216:217], v90 src0_sel:WORD_1
	v_pk_fma_f32 v[206:207], v[172:173], v[214:215], v[206:207] op_sel_hi:[0,1,1]
	v_pk_fma_f32 v[208:209], v[172:173], v[216:217], v[208:209] op_sel_hi:[0,1,1]
	v_cvt_pk_f32_fp8_e32 v[218:219], v91
	v_cvt_pk_f32_fp8_sdwa v[220:221], v91 src0_sel:WORD_1
	v_pk_fma_f32 v[210:211], v[172:173], v[218:219], v[210:211] op_sel_hi:[0,1,1]
	v_pk_fma_f32 v[212:213], v[172:173], v[220:221], v[212:213] op_sel_hi:[0,1,1]
	s_waitcnt vmcnt(28)
	v_cvt_pk_f32_fp8_e32 v[214:215], v92
	v_cvt_pk_f32_fp8_sdwa v[216:217], v92 src0_sel:WORD_1
	v_pk_fma_f32 v[198:199], v[172:173], v[214:215], v[198:199] op_sel:[1,0,0]
	v_pk_fma_f32 v[200:201], v[172:173], v[216:217], v[200:201] op_sel:[1,0,0]
	v_cvt_pk_f32_fp8_e32 v[218:219], v93
	v_cvt_pk_f32_fp8_sdwa v[220:221], v93 src0_sel:WORD_1
	v_pk_fma_f32 v[202:203], v[172:173], v[218:219], v[202:203] op_sel:[1,0,0]
	v_pk_fma_f32 v[204:205], v[172:173], v[220:221], v[204:205] op_sel:[1,0,0]
	v_cvt_pk_f32_fp8_e32 v[214:215], v94
	v_cvt_pk_f32_fp8_sdwa v[216:217], v94 src0_sel:WORD_1
	v_pk_fma_f32 v[206:207], v[172:173], v[214:215], v[206:207] op_sel:[1,0,0]
	v_pk_fma_f32 v[208:209], v[172:173], v[216:217], v[208:209] op_sel:[1,0,0]
	v_cvt_pk_f32_fp8_e32 v[218:219], v95
	v_cvt_pk_f32_fp8_sdwa v[220:221], v95 src0_sel:WORD_1
	v_pk_fma_f32 v[210:211], v[172:173], v[218:219], v[210:211] op_sel:[1,0,0]
	v_pk_fma_f32 v[212:213], v[172:173], v[220:221], v[212:213] op_sel:[1,0,0]
	ds_read_b128 v[170:173], v139 offset:80
	s_waitcnt vmcnt(27)
	v_cvt_pk_f32_fp8_e32 v[214:215], v96
	v_cvt_pk_f32_fp8_sdwa v[216:217], v96 src0_sel:WORD_1
	v_pk_fma_f32 v[198:199], v[174:175], v[214:215], v[198:199] op_sel_hi:[0,1,1]
	v_pk_fma_f32 v[200:201], v[174:175], v[216:217], v[200:201] op_sel_hi:[0,1,1]
	v_cvt_pk_f32_fp8_e32 v[218:219], v97
	v_cvt_pk_f32_fp8_sdwa v[220:221], v97 src0_sel:WORD_1
	v_pk_fma_f32 v[202:203], v[174:175], v[218:219], v[202:203] op_sel_hi:[0,1,1]
	v_pk_fma_f32 v[204:205], v[174:175], v[220:221], v[204:205] op_sel_hi:[0,1,1]
	v_cvt_pk_f32_fp8_e32 v[214:215], v98
	v_cvt_pk_f32_fp8_sdwa v[216:217], v98 src0_sel:WORD_1
	v_pk_fma_f32 v[206:207], v[174:175], v[214:215], v[206:207] op_sel_hi:[0,1,1]
	v_pk_fma_f32 v[208:209], v[174:175], v[216:217], v[208:209] op_sel_hi:[0,1,1]
	v_cvt_pk_f32_fp8_e32 v[218:219], v99
	v_cvt_pk_f32_fp8_sdwa v[220:221], v99 src0_sel:WORD_1
	v_pk_fma_f32 v[210:211], v[174:175], v[218:219], v[210:211] op_sel_hi:[0,1,1]
	v_pk_fma_f32 v[212:213], v[174:175], v[220:221], v[212:213] op_sel_hi:[0,1,1]
	s_waitcnt vmcnt(26)
	v_cvt_pk_f32_fp8_e32 v[214:215], v100
	v_cvt_pk_f32_fp8_sdwa v[216:217], v100 src0_sel:WORD_1
	v_pk_fma_f32 v[198:199], v[174:175], v[214:215], v[198:199] op_sel:[1,0,0]
	v_pk_fma_f32 v[200:201], v[174:175], v[216:217], v[200:201] op_sel:[1,0,0]
	v_cvt_pk_f32_fp8_e32 v[218:219], v101
	v_cvt_pk_f32_fp8_sdwa v[220:221], v101 src0_sel:WORD_1
	v_pk_fma_f32 v[202:203], v[174:175], v[218:219], v[202:203] op_sel:[1,0,0]
	v_pk_fma_f32 v[204:205], v[174:175], v[220:221], v[204:205] op_sel:[1,0,0]
	v_cvt_pk_f32_fp8_e32 v[214:215], v102
	v_cvt_pk_f32_fp8_sdwa v[216:217], v102 src0_sel:WORD_1
	v_pk_fma_f32 v[206:207], v[174:175], v[214:215], v[206:207] op_sel:[1,0,0]
	v_pk_fma_f32 v[208:209], v[174:175], v[216:217], v[208:209] op_sel:[1,0,0]
	v_cvt_pk_f32_fp8_e32 v[218:219], v103
	v_cvt_pk_f32_fp8_sdwa v[220:221], v103 src0_sel:WORD_1
	v_pk_fma_f32 v[210:211], v[174:175], v[218:219], v[210:211] op_sel:[1,0,0]
	v_pk_fma_f32 v[212:213], v[174:175], v[220:221], v[212:213] op_sel:[1,0,0]
	s_waitcnt lgkmcnt(0)
; #define LAS __attribute__((address_space(3)))
; __device__ __forceinline__ void kv8_issue(u32x4 (&buf)[8], __amdgpu_buffer_rsrc_t rs, int voff  , int sbase  , const int (&iv)[4], int b) {
;     const int jj = b >> 3, l0 = (b & 7) * 8;
;     const int ivb = (jj == 0) ? iv[0] : (jj == 1) ? iv[1] : (jj == 2) ? iv[2] : iv[3];
; #pragma unroll
;     for (int u = 0; u < 8; ++u) { const int si = __builtin_amdgcn_readlane(ivb, l0 + u); buf[u] = __builtin_amdgcn_raw_buffer_load_b128(rs, voff, si * 2048 + sbase, KV8_AUX); }
; }
; __device__ __forceinline__ void kv8_pv(const u32x4 (&buf)[8], f32x2v (&o2)[8], const LAS float* srow, int b) {
;     const LAS f32x4* p4 = (const LAS f32x4*)(srow + b * 8);
;     const f32x4 p0 = p4[0], p1 = p4[1];
;     const float p[8] = {p0.x, p0.y, p0.z, p0.w, p1.x, p1.y, p1.z, p1.w};
; #pragma unroll
;     for (int u = 0; u < 8; ++u) {
;         const u32x4 v = buf[u]; const f32x2v pp = {p[u], p[u]};
;         o2[0] = __builtin_elementwise_fma(pp, __builtin_amdgcn_cvt_pk_f32_fp8(v.x, false), o2[0]); o2[1] = __builtin_elementwise_fma(pp, __builtin_amdgcn_cvt_pk_f32_fp8(v.x, true), o2[1]);
;         o2[2] = __builtin_elementwise_fma(pp, __builtin_amdgcn_cvt_pk_f32_fp8(v.y, false), o2[2]); o2[3] = __builtin_elementwise_fma(pp, __builtin_amdgcn_cvt_pk_f32_fp8(v.y, true), o2[3]);
;         o2[4] = __builtin_elementwise_fma(pp, __builtin_amdgcn_cvt_pk_f32_fp8(v.z, false), o2[4]); o2[5] = __builtin_elementwise_fma(pp, __builtin_amdgcn_cvt_pk_f32_fp8(v.z, true), o2[5]);
;         o2[6] = __builtin_elementwise_fma(pp, __builtin_amdgcn_cvt_pk_f32_fp8(v.w, false), o2[6]); o2[7] = __builtin_elementwise_fma(pp, __builtin_amdgcn_cvt_pk_f32_fp8(v.w, true), o2[7]);
;     }
	v_lshl_add_u32 v170, v170, 8, v138
	v_lshl_add_u32 v171, v171, 8, v138
	v_lshl_add_u32 v172, v172, 8, v138
	v_lshl_add_u32 v173, v173, 8, v138
	buffer_load_dwordx4 v[80:83], v170, s[16:19], s26 offen
	buffer_load_dwordx4 v[84:87], v171, s[16:19], s26 offen
	buffer_load_dwordx4 v[88:91], v172, s[16:19], s26 offen
	buffer_load_dwordx4 v[92:95], v173, s[16:19], s26 offen
	s_waitcnt vmcnt(29)
	v_cvt_pk_f32_fp8_e32 v[214:215], v104
	v_cvt_pk_f32_fp8_sdwa v[216:217], v104 src0_sel:WORD_1
	v_pk_fma_f32 v[198:199], v[176:177], v[214:215], v[198:199] op_sel_hi:[0,1,1]
	v_pk_fma_f32 v[200:201], v[176:177], v[216:217], v[200:201] op_sel_hi:[0,1,1]
	v_cvt_pk_f32_fp8_e32 v[218:219], v105
	v_cvt_pk_f32_fp8_sdwa v[220:221], v105 src0_sel:WORD_1
	v_pk_fma_f32 v[202:203], v[176:177], v[218:219], v[202:203] op_sel_hi:[0,1,1]
	v_pk_fma_f32 v[204:205], v[176:177], v[220:221], v[204:205] op_sel_hi:[0,1,1]
	v_cvt_pk_f32_fp8_e32 v[214:215], v106
	v_cvt_pk_f32_fp8_sdwa v[216:217], v106 src0_sel:WORD_1
	v_pk_fma_f32 v[206:207], v[176:177], v[214:215], v[206:207] op_sel_hi:[0,1,1]
	v_pk_fma_f32 v[208:209], v[176:177], v[216:217], v[208:209] op_sel_hi:[0,1,1]
	v_cvt_pk_f32_fp8_e32 v[218:219], v107
	v_cvt_pk_f32_fp8_sdwa v[220:221], v107 src0_sel:WORD_1
	v_pk_fma_f32 v[210:211], v[176:177], v[218:219], v[210:211] op_sel_hi:[0,1,1]
	v_pk_fma_f32 v[212:213], v[176:177], v[220:221], v[212:213] op_sel_hi:[0,1,1]
	s_waitcnt vmcnt(28)
	v_cvt_pk_f32_fp8_e32 v[214:215], v108
	v_cvt_pk_f32_fp8_sdwa v[216:217], v108 src0_sel:WORD_1
	v_pk_fma_f32 v[198:199], v[176:177], v[214:215], v[198:199] op_sel:[1,0,0]
	v_pk_fma_f32 v[200:201], v[176:177], v[216:217], v[200:201] op_sel:[1,0,0]
	v_cvt_pk_f32_fp8_e32 v[218:219], v109
	v_cvt_pk_f32_fp8_sdwa v[220:221], v109 src0_sel:WORD_1
	v_pk_fma_f32 v[202:203], v[176:177], v[218:219], v[202:203] op_sel:[1,0,0]
	v_pk_fma_f32 v[204:205], v[176:177], v[220:221], v[204:205] op_sel:[1,0,0]
	v_cvt_pk_f32_fp8_e32 v[214:215], v110
	v_cvt_pk_f32_fp8_sdwa v[216:217], v110 src0_sel:WORD_1
	v_pk_fma_f32 v[206:207], v[176:177], v[214:215], v[206:207] op_sel:[1,0,0]
	v_pk_fma_f32 v[208:209], v[176:177], v[216:217], v[208:209] op_sel:[1,0,0]
	v_cvt_pk_f32_fp8_e32 v[218:219], v111
	v_cvt_pk_f32_fp8_sdwa v[220:221], v111 src0_sel:WORD_1
	v_pk_fma_f32 v[210:211], v[176:177], v[218:219], v[210:211] op_sel:[1,0,0]
	v_pk_fma_f32 v[212:213], v[176:177], v[220:221], v[212:213] op_sel:[1,0,0]
	ds_read_b128 v[174:177], v139 offset:96
	s_waitcnt vmcnt(27)
	v_cvt_pk_f32_fp8_e32 v[214:215], v112
	v_cvt_pk_f32_fp8_sdwa v[216:217], v112 src0_sel:WORD_1
	v_pk_fma_f32 v[198:199], v[178:179], v[214:215], v[198:199] op_sel_hi:[0,1,1]
	v_pk_fma_f32 v[200:201], v[178:179], v[216:217], v[200:201] op_sel_hi:[0,1,1]
	v_cvt_pk_f32_fp8_e32 v[218:219], v113
	v_cvt_pk_f32_fp8_sdwa v[220:221], v113 src0_sel:WORD_1
	v_pk_fma_f32 v[202:203], v[178:179], v[218:219], v[202:203] op_sel_hi:[0,1,1]
	v_pk_fma_f32 v[204:205], v[178:179], v[220:221], v[204:205] op_sel_hi:[0,1,1]
	v_cvt_pk_f32_fp8_e32 v[214:215], v114
	v_cvt_pk_f32_fp8_sdwa v[216:217], v114 src0_sel:WORD_1
	v_pk_fma_f32 v[206:207], v[178:179], v[214:215], v[206:207] op_sel_hi:[0,1,1]
	v_pk_fma_f32 v[208:209], v[178:179], v[216:217], v[208:209] op_sel_hi:[0,1,1]
	v_cvt_pk_f32_fp8_e32 v[218:219], v115
	v_cvt_pk_f32_fp8_sdwa v[220:221], v115 src0_sel:WORD_1
	v_pk_fma_f32 v[210:211], v[178:179], v[218:219], v[210:211] op_sel_hi:[0,1,1]
	v_pk_fma_f32 v[212:213], v[178:179], v[220:221], v[212:213] op_sel_hi:[0,1,1]
	s_waitcnt vmcnt(26)
	v_cvt_pk_f32_fp8_e32 v[214:215], v116
	v_cvt_pk_f32_fp8_sdwa v[216:217], v116 src0_sel:WORD_1
	v_pk_fma_f32 v[198:199], v[178:179], v[214:215], v[198:199] op_sel:[1,0,0]
	v_pk_fma_f32 v[200:201], v[178:179], v[216:217], v[200:201] op_sel:[1,0,0]
	v_cvt_pk_f32_fp8_e32 v[218:219], v117
	v_cvt_pk_f32_fp8_sdwa v[220:221], v117 src0_sel:WORD_1
	v_pk_fma_f32 v[202:203], v[178:179], v[218:219], v[202:203] op_sel:[1,0,0]
	v_pk_fma_f32 v[204:205], v[178:179], v[220:221], v[204:205] op_sel:[1,0,0]
	v_cvt_pk_f32_fp8_e32 v[214:215], v118
	v_cvt_pk_f32_fp8_sdwa v[216:217], v118 src0_sel:WORD_1
	v_pk_fma_f32 v[206:207], v[178:179], v[214:215], v[206:207] op_sel:[1,0,0]
	v_pk_fma_f32 v[208:209], v[178:179], v[216:217], v[208:209] op_sel:[1,0,0]
	v_cvt_pk_f32_fp8_e32 v[218:219], v119
	v_cvt_pk_f32_fp8_sdwa v[220:221], v119 src0_sel:WORD_1
	v_pk_fma_f32 v[210:211], v[178:179], v[218:219], v[210:211] op_sel:[1,0,0]
	v_pk_fma_f32 v[212:213], v[178:179], v[220:221], v[212:213] op_sel:[1,0,0]
	s_waitcnt lgkmcnt(0)
; __device__ __forceinline__ unsigned cvt_pk_bf16(float lo, float hi) { unsigned r; asm volatile("v_cvt_pk_bf16_f32 %0, %1, %2" : "=v"(r) : "v"(lo), "v"(hi)); return r; }
; #define LAS __attribute__((address_space(3)))
; __device__ __forceinline__ void kv8_pv(const u32x4 (&buf)[8], f32x2v (&o2)[8], const LAS float* srow, int b) {
;     const LAS f32x4* p4 = (const LAS f32x4*)(srow + b * 8);
;     const f32x4 p0 = p4[0], p1 = p4[1];
;     const float p[8] = {p0.x, p0.y, p0.z, p0.w, p1.x, p1.y, p1.z, p1.w};
; #pragma unroll
;     for (int u = 0; u < 8; ++u) {
;         const u32x4 v = buf[u]; const f32x2v pp = {p[u], p[u]};
;         o2[0] = __builtin_elementwise_fma(pp, __builtin_amdgcn_cvt_pk_f32_fp8(v.x, false), o2[0]); o2[1] = __builtin_elementwise_fma(pp, __builtin_amdgcn_cvt_pk_f32_fp8(v.x, true), o2[1]);
;         o2[2] = __builtin_elementwise_fma(pp, __builtin_amdgcn_cvt_pk_f32_fp8(v.y, false), o2[2]); o2[3] = __builtin_elementwise_fma(pp, __builtin_amdgcn_cvt_pk_f32_fp8(v.y, true), o2[3]);
;         o2[4] = __builtin_elementwise_fma(pp, __builtin_amdgcn_cvt_pk_f32_fp8(v.z, false), o2[4]); o2[5] = __builtin_elementwise_fma(pp, __builtin_amdgcn_cvt_pk_f32_fp8(v.z, true), o2[5]);
;         o2[6] = __builtin_elementwise_fma(pp, __builtin_amdgcn_cvt_pk_f32_fp8(v.w, false), o2[6]); o2[7] = __builtin_elementwise_fma(pp, __builtin_amdgcn_cvt_pk_f32_fp8(v.w, true), o2[7]);
;     }
; __device__ __forceinline__ void attn_query8(const unsigned char* __restrict__ KV8, const bf16_t* __restrict__ Z, const int* __restrict__ SEL, bf16_t* __restrict__ YMIX, int t, LAS float* sbuf  ) {
;     ...
;     for (int b = 0; b < nb; b += 3) {
;         kv8_issue(C, rs, lvo, 1024, iv, CLAMPB(b + 2));
;         kv8_pv(A, o, srow, b);
;         kv8_issue(A, rs, lvo, 1024, iv, CLAMPB(b + 3));
;         if (b + 1 < nb) kv8_pv(B, o, srow, b + 1);
;         kv8_issue(B, rs, lvo, 1024, iv, CLAMPB(b + 4));
;         if (b + 2 < nb) kv8_pv(C, o, srow, b + 2);
;     }
;     ...
;     u32x4 o0, o1;
;     o0.x = cvt_pk_bf16(o[0].x, o[0].y); o0.y = cvt_pk_bf16(o[1].x, o[1].y); o0.z = cvt_pk_bf16(o[2].x, o[2].y); o0.w = cvt_pk_bf16(o[3].x, o[3].y);
;     o1.x = cvt_pk_bf16(o[4].x, o[4].y); o1.y = cvt_pk_bf16(o[5].x, o[5].y); o1.z = cvt_pk_bf16(o[6].x, o[6].y); o1.w = cvt_pk_bf16(o[7].x, o[7].y);
;     u32x4* yp = (u32x4*)(YMIX + (size_t)t * D_ + 1024 + lane * 16);
;     yp[0] = o0; yp[1] = o1;
	v_lshl_add_u32 v174, v174, 8, v138
	v_lshl_add_u32 v175, v175, 8, v138
	v_lshl_add_u32 v176, v176, 8, v138
	v_lshl_add_u32 v177, v177, 8, v138
	buffer_load_dwordx4 v[96:99], v174, s[16:19], s26 offen
	buffer_load_dwordx4 v[100:103], v175, s[16:19], s26 offen
	buffer_load_dwordx4 v[104:107], v176, s[16:19], s26 offen
	buffer_load_dwordx4 v[108:111], v177, s[16:19], s26 offen
	s_waitcnt vmcnt(29)
	v_cvt_pk_f32_fp8_e32 v[214:215], v120
	v_cvt_pk_f32_fp8_sdwa v[216:217], v120 src0_sel:WORD_1
	v_pk_fma_f32 v[198:199], v[180:181], v[214:215], v[198:199] op_sel_hi:[0,1,1]
	v_pk_fma_f32 v[200:201], v[180:181], v[216:217], v[200:201] op_sel_hi:[0,1,1]
	v_cvt_pk_f32_fp8_e32 v[218:219], v121
	v_cvt_pk_f32_fp8_sdwa v[220:221], v121 src0_sel:WORD_1
	v_pk_fma_f32 v[202:203], v[180:181], v[218:219], v[202:203] op_sel_hi:[0,1,1]
	v_pk_fma_f32 v[204:205], v[180:181], v[220:221], v[204:205] op_sel_hi:[0,1,1]
	v_cvt_pk_f32_fp8_e32 v[214:215], v122
	v_cvt_pk_f32_fp8_sdwa v[216:217], v122 src0_sel:WORD_1
	v_pk_fma_f32 v[206:207], v[180:181], v[214:215], v[206:207] op_sel_hi:[0,1,1]
	v_pk_fma_f32 v[208:209], v[180:181], v[216:217], v[208:209] op_sel_hi:[0,1,1]
	v_cvt_pk_f32_fp8_e32 v[218:219], v123
	v_cvt_pk_f32_fp8_sdwa v[220:221], v123 src0_sel:WORD_1
	v_pk_fma_f32 v[210:211], v[180:181], v[218:219], v[210:211] op_sel_hi:[0,1,1]
	v_pk_fma_f32 v[212:213], v[180:181], v[220:221], v[212:213] op_sel_hi:[0,1,1]
	s_waitcnt vmcnt(28)
	v_cvt_pk_f32_fp8_e32 v[214:215], v124
	v_cvt_pk_f32_fp8_sdwa v[216:217], v124 src0_sel:WORD_1
	v_pk_fma_f32 v[198:199], v[180:181], v[214:215], v[198:199] op_sel:[1,0,0]
	v_pk_fma_f32 v[200:201], v[180:181], v[216:217], v[200:201] op_sel:[1,0,0]
	v_cvt_pk_f32_fp8_e32 v[218:219], v125
	v_cvt_pk_f32_fp8_sdwa v[220:221], v125 src0_sel:WORD_1
	v_pk_fma_f32 v[202:203], v[180:181], v[218:219], v[202:203] op_sel:[1,0,0]
	v_pk_fma_f32 v[204:205], v[180:181], v[220:221], v[204:205] op_sel:[1,0,0]
	v_cvt_pk_f32_fp8_e32 v[214:215], v126
	v_cvt_pk_f32_fp8_sdwa v[216:217], v126 src0_sel:WORD_1
	v_pk_fma_f32 v[206:207], v[180:181], v[214:215], v[206:207] op_sel:[1,0,0]
	v_pk_fma_f32 v[208:209], v[180:181], v[216:217], v[208:209] op_sel:[1,0,0]
	v_cvt_pk_f32_fp8_e32 v[218:219], v127
	v_cvt_pk_f32_fp8_sdwa v[220:221], v127 src0_sel:WORD_1
	v_pk_fma_f32 v[210:211], v[180:181], v[218:219], v[210:211] op_sel:[1,0,0]
	v_pk_fma_f32 v[212:213], v[180:181], v[220:221], v[212:213] op_sel:[1,0,0]
	ds_read_b128 v[178:181], v139 offset:112
	v_add_f32_dpp v198, v198, v198 row_ror:8 row_mask:0xf bank_mask:0x3
	v_add_f32_dpp v199, v199, v199 row_ror:8 row_mask:0xf bank_mask:0x3
	v_add_f32_dpp v200, v200, v200 row_ror:8 row_mask:0xf bank_mask:0x3
	v_add_f32_dpp v201, v201, v201 row_ror:8 row_mask:0xf bank_mask:0x3
	v_add_f32_dpp v202, v202, v202 row_ror:8 row_mask:0xf bank_mask:0x3
	v_add_f32_dpp v203, v203, v203 row_ror:8 row_mask:0xf bank_mask:0x3
	v_add_f32_dpp v204, v204, v204 row_ror:8 row_mask:0xf bank_mask:0x3
	v_add_f32_dpp v205, v205, v205 row_ror:8 row_mask:0xf bank_mask:0x3
	v_add_f32_dpp v198, v206, v206 row_ror:8 row_mask:0xf bank_mask:0xc
	v_add_f32_dpp v199, v207, v207 row_ror:8 row_mask:0xf bank_mask:0xc
	v_add_f32_dpp v200, v208, v208 row_ror:8 row_mask:0xf bank_mask:0xc
	v_add_f32_dpp v201, v209, v209 row_ror:8 row_mask:0xf bank_mask:0xc
	v_add_f32_dpp v202, v210, v210 row_ror:8 row_mask:0xf bank_mask:0xc
	v_add_f32_dpp v203, v211, v211 row_ror:8 row_mask:0xf bank_mask:0xc
	v_add_f32_dpp v204, v212, v212 row_ror:8 row_mask:0xf bank_mask:0xc
	v_add_f32_dpp v205, v213, v213 row_ror:8 row_mask:0xf bank_mask:0xc
	s_waitcnt lgkmcnt(0)
	v_lshl_add_u32 v178, v178, 8, v138
	v_lshl_add_u32 v179, v179, 8, v138
	v_lshl_add_u32 v180, v180, 8, v138
	v_lshl_add_u32 v181, v181, 8, v138
	buffer_load_dwordx4 v[112:115], v178, s[16:19], s26 offen
	buffer_load_dwordx4 v[116:119], v179, s[16:19], s26 offen
	buffer_load_dwordx4 v[120:123], v180, s[16:19], s26 offen
	buffer_load_dwordx4 v[124:127], v181, s[16:19], s26 offen
	s_nop 1
	v_permlane16_swap_b32_e32 v198, v202
	v_add_f32_e32 v198, v198, v202
	v_permlane16_swap_b32_e32 v199, v203
	v_add_f32_e32 v199, v199, v203
	v_permlane16_swap_b32_e32 v200, v204
	v_add_f32_e32 v200, v200, v204
	v_permlane16_swap_b32_e32 v201, v205
	v_add_f32_e32 v201, v201, v205
	s_nop 0
	v_permlane32_swap_b32_e32 v198, v200
	v_add_f32_e32 v198, v198, v200
	v_permlane32_swap_b32_e32 v199, v201
	v_add_f32_e32 v199, v199, v201
	s_ashr_i32 s81, s80, 31
	s_lshl_b64 s[10:11], s[80:81], 12
	s_add_u32 s10, s14, s10
	s_addc_u32 s11, s15, s11
	v_mul_f32_e32 v198, v198, v149
	v_mul_f32_e32 v199, v199, v149
	v_cvt_pk_bf16_f32 v214, v198, v199
	global_store_dword v238, v214, s[10:11] offset:2048
	s_addk_i32 s80, 0x100
	s_cmpk_gt_i32 s80, 0x3fff
	s_cbranch_scc0 .Latt_unit
	s_waitcnt vmcnt(0)
